# GEMM: static s_setprio 1 on the other wave half (waves 0-3) for comparison with the waves 4-7 raise
# speedup vs baseline: 1.0020x; 1.0020x over previous
.LBB0_741:
	s_and_b64 vcc, exec, s[4:5]
	s_cbranch_vccz .LBB0_813
	s_ashr_i32 s21, s20, 31
	s_lshl_b64 s[92:93], s[20:21], 9
	s_ashr_i32 s4, s2, 31
	s_mul_i32 s4, s92, s4
	s_mul_hi_u32 s5, s92, s2
	s_add_i32 s9, s5, s4
	s_lshr_b64 s[4:5], s[20:21], 23
	s_ashr_i32 s19, s18, 31
	s_mul_i32 s4, s4, s2
	s_lshl_b64 s[94:95], s[18:19], 9
	s_add_i32 s9, s9, s4
	s_ashr_i32 s4, s85, 31
	v_lshlrev_b32_e32 v0, 5, v0
	s_mul_i32 s4, s94, s4
	s_mul_hi_u32 s5, s94, s85
	v_and_b32_e32 v18, 32, v0
	v_mul_i32_i24_e32 v0, 64, v3
	s_add_i32 s12, s5, s4
	s_lshr_b64 s[4:5], s[18:19], 23
	v_lshlrev_b32_e32 v5, 5, v5
	s_ashr_i32 s8, s49, 6
	v_sub_u32_e32 v0, v1, v0
	s_mul_i32 s4, s4, s85
	v_and_b32_e32 v15, 32, v5
	v_lshlrev_b32_e32 v5, 6, v8
	s_ashr_i32 s7, s49, 8
	s_lshl_b64 s[22:23], s[20:21], 8
	s_lshl_b64 s[90:91], s[18:19], 8
	s_lshl_b32 s53, s8, 10
	v_ashrrev_i16_sdwa v0, v228, sext(v0) dst_sel:DWORD dst_unused:UNUSED_PAD src0_sel:DWORD src1_sel:BYTE_0
	s_add_i32 s12, s12, s4
	s_mul_i32 s4, s94, s85
	v_sub_u32_e32 v5, v6, v5
	v_bfe_i32 v19, v0, 0, 16
	s_add_u32 s4, s16, s4
	v_ashrrev_i16_sdwa v5, v228, sext(v5) dst_sel:DWORD dst_unused:UNUSED_PAD src0_sel:DWORD src1_sel:BYTE_0
	v_add_u32_e32 v0, v18, v19
	v_mul_lo_u32 v20, v2, s20
	v_mul_lo_u32 v1, v4, s18
	s_addc_u32 s5, s17, s12
	s_add_i32 s19, s53, 0
	v_bfe_i32 v16, v5, 0, 16
	v_add_lshl_u32 v178, v0, v20, 1
	v_add_lshl_u32 v180, v1, v0, 1
	v_mov_b32_e32 v0, v169
	s_add_i32 m0, s19, 0x10000
	v_add_u32_e32 v5, v15, v16
	v_mul_lo_u32 v6, v9, s18
	s_mul_i32 s11, s92, s2
	global_load_lds_dwordx4 v180, s[4:5]
	s_add_i32 m0, s19, 0x12000
	v_add_lshl_u32 v176, v6, v5, 1
	s_add_u32 s26, s14, s11
	v_mul_lo_u32 v17, v7, s20
	global_load_lds_dwordx4 v176, s[4:5]
	s_addc_u32 s27, s15, s9
	s_mov_b32 m0, s19
	s_add_i32 s21, s19, 0x2000
	v_add_lshl_u32 v174, v5, v17, 1
	global_load_lds_dwordx4 v178, s[26:27]
	s_mov_b32 m0, s21
	s_add_u32 s12, s4, s90
	global_load_lds_dwordx4 v174, s[26:27]
	s_addc_u32 s13, s5, s91
	s_add_i32 m0, s19, 0x14000
	v_mov_b32_e32 v181, v169
	v_mov_b32_e32 v177, v169
	global_load_lds_dwordx4 v180, s[12:13]
	s_add_i32 m0, s19, 0x16000
	v_lshl_add_u64 v[10:11], s[12:13], 0, v[180:181]
	v_lshl_add_u64 v[12:13], s[12:13], 0, v[176:177]
	global_load_lds_dwordx4 v176, s[12:13]
	s_add_u32 s12, s26, s22
	s_addc_u32 s13, s27, s23
	s_add_i32 s64, s19, 0x4000
	s_mov_b32 m0, s64
	s_add_i32 s65, s19, 0x6000
	global_load_lds_dwordx4 v178, s[12:13]
	s_mov_b32 m0, s65
	v_mov_b32_e32 v179, v169
	global_load_lds_dwordx4 v174, s[12:13]
	v_mov_b32_e32 v175, v169
	v_mov_b32_e32 v227, 0x358637bd
	v_lshl_add_u64 v[2:3], s[4:5], 0, v[180:181]
	v_lshl_add_u64 v[4:5], s[4:5], 0, v[176:177]
	v_lshl_add_u64 v[6:7], s[26:27], 0, v[178:179]
	v_lshl_add_u64 v[8:9], s[26:27], 0, v[174:175]
	s_setprio 1
	s_cmp_lg_u32 s7, 1
	s_cbranch_scc1 .LBB0_744
	s_setprio 0
	s_barrier
